# v42: v36 with the attention loop's back edge rotated (loop-back barrier is the loop head; counter, exit test and carried copy sit in front of it; exit path has its own barrier copy)
# baseline (speedup 1.0000x reference)
.LBB0_525:
	s_mul_i32 s7, s7, 0x9800
	s_mul_hi_u32 s8, s6, 0x9800
	s_and_b32 s4, s10, 15
	s_add_i32 s8, s8, s7
	s_mul_i32 s6, s6, 0x9800
	s_add_u32 s6, s50, s6
	s_addc_u32 s7, s51, s8
	s_lshl_b32 s4, s4, 8
	s_add_u32 s48, s6, s4
	s_addc_u32 s49, s7, 0
	s_lshl_b32 s4, s11, 2
	s_bfe_u32 s6, s10, 0x20002
	s_or_b32 s26, s4, s6
	v_mbcnt_lo_u32_b32 v76, -1, 0
	v_mbcnt_hi_u32_b32 v76, -1, v76
	s_mul_i32 s6, s26, 0x210000
	v_add_u32_e32 v54, s39, v76
	v_ashrrev_i32_e32 v16, 4, v54
	s_mul_hi_i32 s4, s26, 0x210000
	s_add_u32 s40, s52, s6
	v_lshlrev_b32_e32 v22, 3, v76
	v_add_u32_e32 v18, 32, v16
	s_addc_u32 s41, s53, s4
	v_and_b32_e32 v0, 0x78, v22
	v_ashrrev_i32_e32 v17, 31, v16
	v_ashrrev_i32_e32 v19, 31, v18
	s_add_u32 s42, s54, s6
	v_lshlrev_b32_e32 v23, 1, v0
	v_lshlrev_b64 v[48:49], 8, v[16:17]
	v_lshlrev_b64 v[8:9], 8, v[18:19]
	s_addc_u32 s43, s55, s4
	v_or_b32_e32 v52, v48, v23
	v_mov_b32_e32 v53, v49
	v_or_b32_e32 v8, v8, v23
	v_lshl_add_u64 v[0:1], s[42:43], 0, v[52:53]
	v_lshl_add_u64 v[4:5], s[42:43], 0, v[8:9]
	v_lshl_add_u64 v[10:11], s[40:41], 0, v[52:53]
	v_lshl_add_u64 v[12:13], s[40:41], 0, v[8:9]
	global_load_dwordx4 v[0:3], v[0:1], off
	s_nop 0
	global_load_dwordx4 v[4:7], v[4:5], off
	s_nop 0
	global_load_dwordx4 v[8:11], v[10:11], off
	s_nop 0
	global_load_dwordx4 v[12:15], v[12:13], off
	v_ashrrev_i32_e32 v55, 1, v54
	s_movk_i32 s4, 0xffe0
	v_bfe_u32 v97, v76, 5, 1
	v_bfi_b32 v17, s4, v55, v76
	v_mov_b64_e32 v[20:21], s[48:49]
	v_mad_i64_i32 v[20:21], s[6:7], v17, s21, v[20:21]
	v_lshlrev_b32_e32 v50, 4, v97
	v_mov_b32_e32 v51, v96
	v_lshl_add_u64 v[20:21], v[20:21], 0, v[50:51]
	global_load_dwordx4 v[118:121], v[20:21], off
	global_load_dwordx4 v[114:117], v[20:21], off offset:32
	global_load_dwordx4 v[126:129], v[20:21], off offset:64
	global_load_dwordx4 v[122:125], v[20:21], off offset:96
	global_load_dwordx4 v[110:113], v[20:21], off offset:128
	global_load_dwordx4 v[106:109], v[20:21], off offset:160
	global_load_dwordx4 v[102:105], v[20:21], off offset:192
	global_load_dwordx4 v[98:101], v[20:21], off offset:224
	v_bfe_u32 v17, v22, 5, 2
	v_and_b32_e32 v22, 0xfffff0, v16
	v_lshlrev_b32_e32 v24, 1, v16
	v_lshrrev_b32_e32 v25, 1, v16
	v_and_b32_e32 v26, 3, v16
	v_and_b32_e32 v19, 0xf0, v54
	v_lshlrev_b32_e32 v16, 8, v16
	v_and_or_b32 v22, v24, 8, v22
	v_bfe_u32 v24, v24, 1, 3
	v_and_b32_e32 v26, 0xfffff0, v18
	v_lshlrev_b32_e32 v27, 1, v18
	v_bitop3_b32 v16, v23, v16, v19 bitop3:0xde
	v_lshlrev_b32_e32 v18, 8, v18
	v_and_b32_e32 v22, 12, v25
	v_and_or_b32 v26, v27, 8, v26
	v_add_u32_e32 v188, 0, v16
	v_bitop3_b32 v16, v18, v23, v19 bitop3:0xf6
	v_or_b32_e32 v18, v22, v17
	v_and_or_b32 v19, v25, 12, 16
	v_and_b32_e32 v25, 48, v23
	v_lshlrev_b32_e32 v24, 6, v24
	v_add_u32_e32 v189, 0, v16
	v_lshlrev_b32_e32 v16, 9, v18
	v_or_b32_e32 v17, v19, v17
	v_or3_b32 v16, v16, v24, v25
	v_lshlrev_b32_e32 v17, 9, v17
	v_and_b32_e32 v180, 31, v76
	v_lshlrev_b32_e32 v51, 4, v76
	v_or3_b32 v17, v17, v24, v25
	v_add_u32_e32 v190, 0, v16
	v_add_u32_e32 v191, 0, v17
	s_waitcnt vmcnt(0)
	s_add_i32 s4, 0, 0x10000
	s_mov_b64 s[6:7], 0x6000
	v_and_b32_e32 v181, 0xffffffe0, v55
	v_and_b32_e32 v77, 63, v76
	s_mov_b32 s8, s5
	s_mov_b32 s9, s5
	s_mov_b32 s10, s5
	s_mov_b32 s11, s5
	s_mov_b32 s12, s5
	s_waitcnt vmcnt(0)
	ds_write_b128 v190, v[0:3]
	s_waitcnt vmcnt(10)
	ds_write_b128 v191, v[4:7]
	s_waitcnt vmcnt(9)
	ds_write_b128 v188, v[8:11] offset:32768
	s_waitcnt vmcnt(8)
	ds_write_b128 v189, v[12:15] offset:32768
	v_lshlrev_b32_e32 v12, 8, v180
	v_and_b32_e32 v13, 0xf0, v51
	v_bitop3_b32 v0, v50, v12, v13 bitop3:0xde
	v_add_u32_e32 v192, 0, v0
	s_waitcnt lgkmcnt(0)
	s_barrier
	ds_read_b128 v[0:3], v192 offset:32768
	ds_read_b128 v[4:7], v192 offset:40960
	s_waitcnt vmcnt(7) lgkmcnt(1)
	v_mfma_f32_32x32x16_bf16 v[16:31], v[0:3], v[118:121], 0
	v_or_b32_e32 v0, 32, v50
	v_bitop3_b32 v0, v0, v12, v13 bitop3:0xde
	v_add_u32_e32 v200, 0, v0
	v_lshl_add_u64 v[8:9], v[52:53], 0, s[6:7]
	v_lshl_add_u64 v[10:11], s[42:43], 0, v[8:9]
	v_lshlrev_b32_e32 v14, 3, v77
	v_and_b32_e32 v15, 0xc0, v51
	s_waitcnt lgkmcnt(0)
	v_mfma_f32_32x32x16_bf16 v[32:47], v[4:7], v[118:121], 0
	ds_read_b128 v[0:3], v200 offset:32768
	ds_read_b128 v[4:7], v200 offset:40960
	s_mov_b32 s6, s5
	s_mov_b32 s7, s5
	s_mov_b32 s13, s5
	s_mov_b32 s14, s5
	s_mov_b32 s15, s5
	s_mov_b32 s16, s5
	s_waitcnt vmcnt(6) lgkmcnt(1)
	v_mfma_f32_32x32x16_bf16 v[16:31], v[0:3], v[114:117], v[16:31]
	v_or_b32_e32 v0, 64, v50
	v_bitop3_b32 v0, v0, v12, v13 bitop3:0xde
	v_add_u32_e32 v199, 0, v0
	s_mov_b32 s17, s5
	s_mov_b32 s18, s5
	s_mov_b32 s19, s5
	s_cmp_lg_u32 0, -1
	s_waitcnt lgkmcnt(0)
	v_mfma_f32_32x32x16_bf16 v[32:47], v[4:7], v[114:117], v[32:47]
	ds_read_b128 v[0:3], v199 offset:32768
	ds_read_b128 v[4:7], v199 offset:40960
	s_cselect_b32 s27, 0, 0
	v_lshlrev_b32_e32 v183, 2, v97
	v_mov_b32_e32 v185, 0
	s_waitcnt vmcnt(5) lgkmcnt(1)
	v_mfma_f32_32x32x16_bf16 v[16:31], v[0:3], v[126:129], v[16:31]
	v_or_b32_e32 v0, 0x60, v50
	v_bitop3_b32 v0, v0, v12, v13 bitop3:0xde
	v_add_u32_e32 v198, 0, v0
	s_waitcnt lgkmcnt(0)
	v_mfma_f32_32x32x16_bf16 v[32:47], v[4:7], v[126:129], v[32:47]
	ds_read_b128 v[0:3], v198 offset:32768
	ds_read_b128 v[4:7], v198 offset:40960
	s_waitcnt vmcnt(4) lgkmcnt(1)
	v_mfma_f32_32x32x16_bf16 v[16:31], v[0:3], v[122:125], v[16:31]
	v_or_b32_e32 v0, 0x80, v50
	v_bitop3_b32 v0, v0, v12, v13 bitop3:0xde
	v_add_u32_e32 v195, 0, v0
	s_waitcnt lgkmcnt(0)
	v_mfma_f32_32x32x16_bf16 v[32:47], v[4:7], v[122:125], v[32:47]
	ds_read_b128 v[0:3], v195 offset:32768
	ds_read_b128 v[4:7], v195 offset:40960
	s_waitcnt vmcnt(3) lgkmcnt(1)
	v_mfma_f32_32x32x16_bf16 v[16:31], v[0:3], v[110:113], v[16:31]
	v_or_b32_e32 v0, 0xa0, v50
	v_bitop3_b32 v0, v0, v12, v13 bitop3:0xde
	v_add_u32_e32 v193, 0, v0
	ds_read_b128 v[0:3], v193 offset:32768
	s_waitcnt lgkmcnt(1)
	v_mfma_f32_32x32x16_bf16 v[32:47], v[4:7], v[110:113], v[32:47]
	v_and_b32_e32 v4, 0x3fffffc0, v54
	v_lshl_add_u32 v78, v4, 2, s4
	ds_read_b128 v[4:7], v193 offset:40960
	s_mov_b32 s4, s5
	v_add_u32_e32 v182, v78, v50
	v_lshl_add_u32 v184, v180, 2, v78
	s_waitcnt vmcnt(2) lgkmcnt(1)
	v_mfma_f32_32x32x16_bf16 v[16:31], v[0:3], v[106:109], v[16:31]
	v_lshl_add_u64 v[0:1], v[52:53], 0, s[68:69]
	v_lshl_add_u64 v[2:3], s[42:43], 0, v[0:1]
	v_lshl_add_u64 v[0:1], s[40:41], 0, v[0:1]
	global_load_dwordx4 v[54:57], v[2:3], off
	global_load_dwordx4 v[58:61], v[10:11], off
	v_lshl_add_u64 v[2:3], s[40:41], 0, v[8:9]
	global_load_dwordx4 v[62:65], v[0:1], off
	global_load_dwordx4 v[66:69], v[2:3], off
	v_or_b32_e32 v0, 0xc0, v50
	v_bitop3_b32 v0, v0, v12, v13 bitop3:0xde
	v_add_u32_e32 v202, 0, v0
	ds_read_b128 v[0:3], v202 offset:32768
	v_lshlrev_b32_e32 v9, 1, v76
	v_and_or_b32 v8, v14, 24, v15
	s_waitcnt lgkmcnt(1)
	v_mfma_f32_32x32x16_bf16 v[32:47], v[4:7], v[106:109], v[32:47]
	v_and_b32_e32 v4, 32, v9
	v_and_b32_e32 v5, 0x100, v14
	v_or3_b32 v51, v8, v4, v5
	ds_read_b128 v[4:7], v202 offset:40960
	v_add_u32_e32 v187, s27, v51
	s_waitcnt vmcnt(5) lgkmcnt(1)
	v_mfma_f32_32x32x16_bf16 v[16:31], v[0:3], v[102:105], v[16:31]
	v_or_b32_e32 v0, 0xe0, v50
	v_bitop3_b32 v0, v0, v12, v13 bitop3:0xde
	v_add_u32_e32 v201, 0, v0
	ds_read_b128 v[0:3], v201 offset:32768
	ds_read_b128 v[70:73], v201 offset:40960
	s_waitcnt lgkmcnt(2)
	v_mfma_f32_32x32x16_bf16 v[32:47], v[4:7], v[102:105], v[32:47]
	s_waitcnt vmcnt(4) lgkmcnt(1)
	v_mfma_f32_32x32x16_bf16 v[16:31], v[0:3], v[98:101], v[16:31]
	v_mov_b64_e32 v[0:1], s[4:5]
	v_mov_b64_e32 v[2:3], s[6:7]
	v_mov_b64_e32 v[4:5], s[8:9]
	v_mov_b64_e32 v[6:7], s[10:11]
	v_mov_b64_e32 v[8:9], s[12:13]
	v_mov_b64_e32 v[10:11], s[14:15]
	v_mov_b64_e32 v[12:13], s[16:17]
	s_waitcnt lgkmcnt(0)
	v_mfma_f32_32x32x16_bf16 v[32:47], v[70:73], v[98:101], v[32:47]
	s_nop 2
	v_max_f32_e32 v70, v17, v17
	v_max_f32_e32 v71, v16, v16
	v_max_f32_e32 v70, v71, v70
	v_max3_f32 v70, v70, v18, v19
	v_max3_f32 v70, v70, v20, v21
	v_max3_f32 v70, v70, v22, v23
	v_max3_f32 v70, v70, v24, v25
	v_max3_f32 v70, v70, v26, v27
	v_max3_f32 v70, v70, v28, v29
	v_max3_f32 v70, v70, v30, v31
	v_max3_f32 v70, v70, v32, v33
	v_max3_f32 v70, v70, v34, v35
	v_max3_f32 v70, v70, v36, v37
	v_max3_f32 v70, v70, v38, v39
	v_max3_f32 v70, v70, v40, v41
	v_max3_f32 v70, v70, v42, v43
	v_mov_b64_e32 v[14:15], s[18:19]
	v_max3_f32 v70, v70, v44, v45
	s_mov_b64 s[6:7], 0x8000
	v_max3_f32 v79, v70, v46, v47
	v_lshl_add_u64 v[70:71], v[52:53], 0, s[6:7]
	s_mov_b64 s[6:7], 0xa000
	v_lshl_add_u64 v[72:73], s[42:43], 0, v[70:71]
	v_lshl_add_u64 v[52:53], v[52:53], 0, s[6:7]
	v_lshl_add_u64 v[70:71], s[40:41], 0, v[70:71]
	v_lshl_add_u64 v[74:75], s[42:43], 0, v[52:53]
	global_load_dwordx4 v[130:133], v[72:73], off
	global_load_dwordx4 v[138:141], v[74:75], off
	v_lshl_add_u64 v[52:53], s[40:41], 0, v[52:53]
	global_load_dwordx4 v[134:137], v[70:71], off
	global_load_dwordx4 v[142:145], v[52:53], off
	v_mov_b32_e32 v80, v79
	s_nop 1
	v_permlane32_swap_b32_e32 v79, v80
	v_max_f32_e32 v52, v80, v80
	v_max_f32_e32 v53, v79, v79
	v_max_f32_e32 v52, v53, v52
	v_add_f32_e32 v53, 0x7149f2ca, v52
	v_max_f32_e32 v52, 0xf149f2ca, v52
	v_cmp_ge_f32_e32 vcc, s92, v53
	v_sub_f32_e32 v53, 0xf149f2ca, v52
	v_mul_f32_e32 v53, 0x3e0293ee, v53
	v_exp_f32_e32 v53, v53
	s_cmp_eq_u64 vcc, exec
	s_cselect_b64 vcc, -1, 0
	s_waitcnt vmcnt(4)
	v_cndmask_b32_e64 v203, v53, 1.0, vcc
	v_mov_b32_e32 v53, 0xf149f2ca
	v_cndmask_b32_e32 v170, v52, v53, vcc
	v_mul_f32_e32 v52, 0xbe0293ee, v170
	v_fmamk_f32 v16, v16, 0x3e0293ee, v52
	v_exp_f32_e32 v163, v16
	v_fmamk_f32 v16, v17, 0x3e0293ee, v52
	v_exp_f32_e32 v177, v16
	v_fmamk_f32 v16, v18, 0x3e0293ee, v52
	v_exp_f32_e32 v164, v16
	v_fmamk_f32 v16, v19, 0x3e0293ee, v52
	v_exp_f32_e32 v207, v16
	v_fmamk_f32 v16, v20, 0x3e0293ee, v52
	v_exp_f32_e32 v176, v16
	v_fmamk_f32 v16, v21, 0x3e0293ee, v52
	v_exp_f32_e32 v210, v16
	v_fmamk_f32 v16, v22, 0x3e0293ee, v52
	v_exp_f32_e32 v165, v16
	v_fmamk_f32 v16, v23, 0x3e0293ee, v52
	v_exp_f32_e32 v175, v16
	v_fmamk_f32 v16, v24, 0x3e0293ee, v52
	v_exp_f32_e32 v166, v16
	v_fmamk_f32 v16, v25, 0x3e0293ee, v52
	v_exp_f32_e32 v173, v16
	v_fmamk_f32 v16, v26, 0x3e0293ee, v52
	v_exp_f32_e32 v167, v16
	v_fmamk_f32 v16, v27, 0x3e0293ee, v52
	v_exp_f32_e32 v174, v16
	v_fmamk_f32 v16, v28, 0x3e0293ee, v52
	v_exp_f32_e32 v168, v16
	v_fmamk_f32 v16, v29, 0x3e0293ee, v52
	v_exp_f32_e32 v171, v16
	v_fmamk_f32 v16, v30, 0x3e0293ee, v52
	v_pk_fma_f32 v[146:147], v[46:47], s[88:89], v[52:53] op_sel_hi:[1,0,0]
	v_pk_fma_f32 v[152:153], v[44:45], s[88:89], v[52:53] op_sel_hi:[1,0,0]
	v_pk_fma_f32 v[156:157], v[42:43], s[88:89], v[52:53] op_sel_hi:[1,0,0]
	v_pk_fma_f32 v[148:149], v[40:41], s[88:89], v[52:53] op_sel_hi:[1,0,0]
	v_pk_fma_f32 v[150:151], v[38:39], s[88:89], v[52:53] op_sel_hi:[1,0,0]
	v_pk_fma_f32 v[154:155], v[36:37], s[88:89], v[52:53] op_sel_hi:[1,0,0]
	v_pk_fma_f32 v[158:159], v[34:35], s[88:89], v[52:53] op_sel_hi:[1,0,0]
	v_pk_fma_f32 v[160:161], v[32:33], s[88:89], v[52:53] op_sel_hi:[1,0,0]
	v_exp_f32_e32 v169, v16
	v_fmac_f32_e32 v52, 0x3e0293ee, v31
	v_mov_b32_e32 v16, 0x210000
	v_exp_f32_e32 v172, v52
	v_mad_i64_i32 v[16:17], s[6:7], s26, v16, v[48:49]
	v_and_b32_e32 v18, 15, v76
	s_addk_i32 s27, 0x4000
	v_lshl_or_b32 v16, v18, 4, v16
	s_waitcnt vmcnt(7)
	ds_write_b128 v190, v[54:57] offset:16384
	s_waitcnt vmcnt(6)
	ds_write_b128 v191, v[58:61] offset:16384
	s_waitcnt vmcnt(5)
	ds_write_b128 v188, v[62:65] offset:49152
	s_waitcnt vmcnt(4)
	ds_write_b128 v189, v[66:69] offset:49152
	v_add_u32_e32 v186, s27, v51
	v_lshl_add_u64 v[178:179], s[46:47], 0, v[16:17]
	v_mov_b64_e32 v[62:63], v[14:15]
	v_mov_b64_e32 v[46:47], v[14:15]
	v_mov_b64_e32 v[30:31], v[14:15]
	v_cmp_gt_u32_e64 s[40:41], 32, v77
	v_mov_b64_e32 v[60:61], v[12:13]
	v_mov_b64_e32 v[58:59], v[10:11]
	v_mov_b64_e32 v[56:57], v[8:9]
	v_mov_b64_e32 v[54:55], v[6:7]
	v_mov_b64_e32 v[52:53], v[4:5]
	v_mov_b64_e32 v[50:51], v[2:3]
	v_mov_b64_e32 v[48:49], v[0:1]
	v_mov_b64_e32 v[44:45], v[12:13]
	v_mov_b64_e32 v[42:43], v[10:11]
	v_mov_b64_e32 v[40:41], v[8:9]
	v_mov_b64_e32 v[38:39], v[6:7]
	v_mov_b64_e32 v[36:37], v[4:5]
	v_mov_b64_e32 v[34:35], v[2:3]
	v_mov_b64_e32 v[32:33], v[0:1]
	v_mov_b64_e32 v[28:29], v[12:13]
	v_mov_b64_e32 v[26:27], v[10:11]
	v_mov_b64_e32 v[24:25], v[8:9]
	v_mov_b64_e32 v[22:23], v[6:7]
	v_mov_b64_e32 v[20:21], v[4:5]
	v_mov_b64_e32 v[18:19], v[2:3]
	v_mov_b64_e32 v[16:17], v[0:1]
	s_waitcnt lgkmcnt(0)
	v_readfirstlane_b32 s66, v178
	v_readfirstlane_b32 s67, v179
	s_nop 3
	v_subrev_u32_e32 v178, s66, v178
	v_add_u32_e32 v179, 0x2000, v178
	s_add_u32 s98, s66, 0xfef7a000
	s_addc_u32 s99, s67, -1
	s_add_u32 s66, s66, 0xffffa000
	s_addc_u32 s67, s67, -1
	v_mov_b32_e32 v243, v170
	v_mul_f32_e32 v242, 0xbe0293ee, v243
	s_mov_b32 s100, 0
	s_mov_b32 s101, 0x14000
.LBB0_526:
	s_barrier
	ds_read_b128 v[64:67], v192 offset:49152
	ds_read_b128 v[68:71], v192 offset:57344
	ds_read_b128 v[232:235], v200 offset:49152
	ds_read_b128 v[236:239], v200 offset:57344
	ds_read_b128 v[250:253], v199 offset:49152
	ds_read_b128 v[244:247], v199 offset:57344
	ds_read_b128 v[212:215], v198 offset:49152
	ds_read_b128 v[216:219], v198 offset:57344
	v_add_u32_e32 v186, s100, v187
	v_add_f32_e32 v162, v163, v177
	s_waitcnt lgkmcnt(6)
	v_mfma_f32_32x32x16_bf16 v[80:95], v[64:67], v[118:121], 0
	v_add_f32_e32 v162, v164, v162
	v_add_f32_e32 v162, v207, v162
	v_add_f32_e32 v162, v176, v162
	v_add_f32_e32 v162, v210, v162
	v_mfma_f32_32x32x16_bf16 v[64:79], v[68:71], v[118:121], 0
	v_add_f32_e32 v162, v165, v162
	v_add_f32_e32 v162, v175, v162
	v_add_f32_e32 v162, v166, v162
	v_add_f32_e32 v162, v173, v162
	v_add_f32_e32 v162, v167, v162
	s_waitcnt lgkmcnt(4)
	v_mfma_f32_32x32x16_bf16 v[80:95], v[232:235], v[114:117], v[80:95]
	ds_read_b128 v[232:235], v195 offset:49152
	v_add_f32_e32 v162, v174, v162
	v_exp_f32_e32 v160, v160
	v_add_f32_e32 v162, v168, v162
	v_exp_f32_e32 v161, v161
	v_mfma_f32_32x32x16_bf16 v[64:79], v[236:239], v[114:117], v[64:79]
	ds_read_b128 v[236:239], v195 offset:57344
	v_add_f32_e32 v162, v171, v162
	v_exp_f32_e32 v158, v158
	v_add_f32_e32 v162, v169, v162
	v_exp_f32_e32 v159, v159
	s_waitcnt lgkmcnt(4)
	v_mfma_f32_32x32x16_bf16 v[80:95], v[250:253], v[126:129], v[80:95]
	ds_read_b128 v[250:253], v193 offset:49152
	v_add_f32_e32 v162, v172, v162
	v_exp_f32_e32 v154, v154
	v_add_f32_e32 v162, v160, v162
	v_exp_f32_e32 v155, v155
	v_mfma_f32_32x32x16_bf16 v[64:79], v[244:247], v[126:129], v[64:79]
	ds_read_b128 v[244:247], v193 offset:57344
	v_add_f32_e32 v162, v161, v162
	v_exp_f32_e32 v150, v150
	v_add_f32_e32 v162, v158, v162
	v_exp_f32_e32 v151, v151
	s_waitcnt lgkmcnt(4)
	v_mfma_f32_32x32x16_bf16 v[80:95], v[212:215], v[122:125], v[80:95]
	ds_read_b128 v[212:215], v202 offset:49152
	v_add_f32_e32 v162, v159, v162
	v_exp_f32_e32 v148, v148
	v_add_f32_e32 v162, v154, v162
	v_exp_f32_e32 v149, v149
	v_mfma_f32_32x32x16_bf16 v[64:79], v[216:219], v[122:125], v[64:79]
	ds_read_b128 v[216:219], v202 offset:57344
	v_add_f32_e32 v162, v155, v162
	v_exp_f32_e32 v156, v156
	v_add_f32_e32 v162, v150, v162
	v_exp_f32_e32 v157, v157
	s_waitcnt lgkmcnt(4)
	v_mfma_f32_32x32x16_bf16 v[80:95], v[232:235], v[110:113], v[80:95]
	ds_read_b128 v[232:235], v201 offset:49152
	v_add_f32_e32 v162, v151, v162
	v_exp_f32_e32 v152, v152
	v_add_f32_e32 v162, v148, v162
	v_exp_f32_e32 v153, v153
	v_mfma_f32_32x32x16_bf16 v[64:79], v[236:239], v[110:113], v[64:79]
	ds_read_b128 v[236:239], v201 offset:57344
	v_add_f32_e32 v162, v149, v162
	v_exp_f32_e32 v146, v146
	v_add_f32_e32 v162, v156, v162
	v_exp_f32_e32 v147, v147
	s_waitcnt lgkmcnt(4)
	v_mfma_f32_32x32x16_bf16 v[80:95], v[250:253], v[106:109], v[80:95]
	v_add_f32_e32 v162, v157, v162
	v_add_f32_e32 v162, v152, v162
	v_add_f32_e32 v162, v153, v162
	v_add_f32_e32 v162, v146, v162
	v_add_f32_e32 v204, v147, v162
	v_mov_b32_e32 v205, v204
	v_mfma_f32_32x32x16_bf16 v[64:79], v[244:247], v[106:109], v[64:79]
	s_nop 0
	v_permlane32_swap_b32_e32 v204, v205
	v_cvt_pk_bf16_f32 v162, v163, v177
	v_cvt_pk_bf16_f32 v163, v164, v207
	v_cvt_pk_bf16_f32 v164, v176, v210
	s_waitcnt lgkmcnt(2)
	v_mfma_f32_32x32x16_bf16 v[80:95], v[212:215], v[102:105], v[80:95]
	v_cvt_pk_bf16_f32 v165, v165, v175
	v_cvt_pk_bf16_f32 v166, v166, v173
	v_cvt_pk_bf16_f32 v167, v167, v174
	v_cvt_pk_bf16_f32 v168, v168, v171
	v_mfma_f32_32x32x16_bf16 v[64:79], v[216:219], v[102:105], v[64:79]
	v_cvt_pk_bf16_f32 v169, v169, v172
	v_cvt_pk_bf16_f32 v172, v160, v161
	v_cvt_pk_bf16_f32 v173, v158, v159
	v_cvt_pk_bf16_f32 v174, v154, v155
	ds_read_b64_tr_b16 v[210:211], v186 offset:0x0
	ds_read_b64_tr_b16 v[212:213], v186 offset:0x800
	ds_read_b64_tr_b16 v[214:215], v186 offset:0x200
	ds_read_b64_tr_b16 v[216:217], v186 offset:0xa00
	ds_read_b64_tr_b16 v[218:219], v186 offset:0x400
	ds_read_b64_tr_b16 v[220:221], v186 offset:0xc00
	ds_read_b64_tr_b16 v[222:223], v186 offset:0x600
	ds_read_b64_tr_b16 v[224:225], v186 offset:0xe00
	s_waitcnt lgkmcnt(8)
	v_mfma_f32_32x32x16_bf16 v[80:95], v[232:235], v[98:101], v[80:95]
	v_cvt_pk_bf16_f32 v175, v150, v151
	v_cvt_pk_bf16_f32 v206, v148, v149
	v_cvt_pk_bf16_f32 v207, v156, v157
	v_mfma_f32_32x32x16_bf16 v[64:79], v[236:239], v[98:101], v[64:79]
	v_cvt_pk_bf16_f32 v208, v152, v153
	v_cvt_pk_bf16_f32 v209, v146, v147
	s_waitcnt vmcnt(0)
	ds_write_b128 v188, v[134:137] offset:32768
	ds_write_b128 v189, v[142:145] offset:32768
	global_load_dwordx4 v[146:149], v178, s[66:67]
	global_load_dwordx4 v[150:153], v179, s[66:67]
	global_load_dwordx4 v[154:157], v178, s[98:99]
	global_load_dwordx4 v[158:161], v179, s[98:99]
	s_add_u32 s66, s66, 0x4000
	s_addc_u32 s67, s67, 0
	s_add_u32 s98, s98, 0x4000
	s_addc_u32 s99, s99, 0
	s_waitcnt lgkmcnt(6)
	v_mfma_f32_32x32x16_bf16 v[0:15], v[162:165], v[210:213], v[0:15]
	ds_read_b64_tr_b16 v[210:211], v186 offset:0x1000
	ds_read_b64_tr_b16 v[212:213], v186 offset:0x1800
	v_max_f32_e32 v240, v80, v81
	v_max3_f32 v240, v240, v82, v83
	v_max3_f32 v240, v240, v84, v85
	v_max3_f32 v240, v240, v86, v87
	v_max3_f32 v240, v240, v88, v89
	v_mfma_f32_32x32x16_bf16 v[48:63], v[162:165], v[214:217], v[48:63]
	ds_read_b64_tr_b16 v[214:215], v186 offset:0x1200
	ds_read_b64_tr_b16 v[216:217], v186 offset:0x1a00
	v_max3_f32 v240, v240, v90, v91
	v_max3_f32 v240, v240, v92, v93
	v_max3_f32 v240, v240, v94, v95
	v_max3_f32 v240, v240, v64, v65
	v_max3_f32 v240, v240, v66, v67
	v_max3_f32 v240, v240, v68, v69
	s_waitcnt lgkmcnt(6)
	v_mfma_f32_32x32x16_bf16 v[32:47], v[162:165], v[218:221], v[32:47]
	ds_read_b64_tr_b16 v[218:219], v186 offset:0x1400
	ds_read_b64_tr_b16 v[220:221], v186 offset:0x1c00
	v_max3_f32 v240, v240, v70, v71
	v_max3_f32 v240, v240, v72, v73
	v_max3_f32 v240, v240, v74, v75
	v_max3_f32 v240, v240, v76, v77
	v_max3_f32 v240, v240, v78, v79
	v_mfma_f32_32x32x16_bf16 v[16:31], v[162:165], v[222:225], v[16:31]
	ds_read_b64_tr_b16 v[222:223], v186 offset:0x1600
	ds_read_b64_tr_b16 v[224:225], v186 offset:0x1e00
	v_mov_b32_e32 v241, v240
	s_nop 1
	v_permlane32_swap_b32_e32 v240, v241
	v_max_f32_e32 v240, v240, v241
	v_sub_f32_e32 v241, v240, v243
	v_cmp_ge_f32_e32 vcc, s92, v241
	s_waitcnt lgkmcnt(4)
	v_mfma_f32_32x32x16_bf16 v[0:15], v[166:169], v[210:213], v[0:15]
	ds_read_b64_tr_b16 v[210:211], v186 offset:0x2000
	ds_read_b64_tr_b16 v[212:213], v186 offset:0x2800
	s_cmp_eq_u64 vcc, exec
	s_cselect_b64 s[42:43], -1, 0
	s_cbranch_scc1 .Lattn_common_a
	v_max_f32_e32 v240, v243, v240
	v_sub_f32_e32 v241, v243, v240
	v_mul_f32_e32 v241, 0x3e0293ee, v241
	v_exp_f32_e32 v241, v241
	v_mov_b32_e32 v243, v240
	v_mul_f32_e32 v242, 0xbe0293ee, v243

.LBB0_536:
	s_add_i32 s100, s100, s101
	s_sub_i32 s100, 0x18000, s100
	v_pk_fma_f32 v[160:161], v[64:65], s[88:89], v[242:243] op_sel_hi:[1,0,0]
	v_add_f32_e32 v64, v204, v205
	v_fmac_f32_e32 v64, v203, v185
	v_add_f32_e32 v185, v208, v209
	v_pk_fma_f32 v[158:159], v[66:67], s[88:89], v[242:243] op_sel_hi:[1,0,0]
	v_pk_fma_f32 v[154:155], v[68:69], s[88:89], v[242:243] op_sel_hi:[1,0,0]
	v_pk_fma_f32 v[150:151], v[70:71], s[88:89], v[242:243] op_sel_hi:[1,0,0]
	v_pk_fma_f32 v[148:149], v[72:73], s[88:89], v[242:243] op_sel_hi:[1,0,0]
	v_pk_fma_f32 v[156:157], v[74:75], s[88:89], v[242:243] op_sel_hi:[1,0,0]
	v_pk_fma_f32 v[152:153], v[76:77], s[88:89], v[242:243] op_sel_hi:[1,0,0]
	v_pk_fma_f32 v[146:147], v[78:79], s[88:89], v[242:243] op_sel_hi:[1,0,0]
	v_fmac_f32_e32 v185, v64, v206
	s_add_i32 s34, s34, 2
	s_and_b64 vcc, exec, s[6:7]
	v_mov_b32_e32 v203, v162
	s_waitcnt lgkmcnt(0)
	s_cbranch_vccnz .Lattn_exit_bar
	s_branch .LBB0_526
.Lattn_exit_bar:
	s_barrier
.LBB0_538:
	v_mov_b32_e32 v170, v243
	s_add_i32 vcc_lo, s100, s101
	s_sub_i32 vcc_lo, 0x18000, vcc_lo
	v_add_u32_e32 v186, vcc_lo, v187
	v_add_u32_e32 v187, s100, v187
	ds_read_b128 v[64:67], v192 offset:49152
	ds_read_b128 v[68:71], v192 offset:57344
	s_waitcnt lgkmcnt(1)
	v_mfma_f32_32x32x16_bf16 v[80:95], v[64:67], v[118:121], 0
	s_waitcnt lgkmcnt(0)
	v_mfma_f32_32x32x16_bf16 v[64:79], v[68:71], v[118:121], 0
	ds_read_b128 v[118:121], v200 offset:49152
	ds_read_b128 v[130:133], v200 offset:57344
	s_waitcnt lgkmcnt(1)
	v_mfma_f32_32x32x16_bf16 v[80:95], v[118:121], v[114:117], v[80:95]
	s_waitcnt lgkmcnt(0)
	v_mfma_f32_32x32x16_bf16 v[64:79], v[130:133], v[114:117], v[64:79]
	ds_read_b128 v[114:117], v199 offset:49152
	ds_read_b128 v[118:121], v199 offset:57344
	s_waitcnt lgkmcnt(1)
	v_mfma_f32_32x32x16_bf16 v[80:95], v[114:117], v[126:129], v[80:95]
	s_waitcnt lgkmcnt(0)
	v_mfma_f32_32x32x16_bf16 v[64:79], v[118:121], v[126:129], v[64:79]
	ds_read_b128 v[114:117], v198 offset:49152
	ds_read_b128 v[118:121], v198 offset:57344
	s_waitcnt lgkmcnt(1)
	v_mfma_f32_32x32x16_bf16 v[80:95], v[114:117], v[122:125], v[80:95]
	s_waitcnt lgkmcnt(0)
	v_mfma_f32_32x32x16_bf16 v[64:79], v[118:121], v[122:125], v[64:79]
	ds_read_b128 v[114:117], v195 offset:49152
	ds_read_b128 v[118:121], v195 offset:57344
	v_exp_f32_e32 v122, v146
	v_exp_f32_e32 v123, v147
	s_waitcnt lgkmcnt(1)
	v_mfma_f32_32x32x16_bf16 v[80:95], v[114:117], v[110:113], v[80:95]
	s_waitcnt lgkmcnt(0)
	v_mfma_f32_32x32x16_bf16 v[64:79], v[118:121], v[110:113], v[64:79]
	ds_read_b128 v[110:113], v193 offset:49152
	ds_read_b128 v[114:117], v193 offset:57344
	v_exp_f32_e32 v118, v156
	v_exp_f32_e32 v119, v157
	v_exp_f32_e32 v120, v152
	v_exp_f32_e32 v121, v153
	s_waitcnt lgkmcnt(1)
	v_mfma_f32_32x32x16_bf16 v[80:95], v[110:113], v[106:109], v[80:95]
	s_waitcnt lgkmcnt(0)
	v_mfma_f32_32x32x16_bf16 v[64:79], v[114:117], v[106:109], v[64:79]
	ds_read_b128 v[106:109], v202 offset:49152
	ds_read_b128 v[110:113], v202 offset:57344
	v_exp_f32_e32 v114, v150
	v_exp_f32_e32 v115, v151
	v_exp_f32_e32 v116, v148
	v_exp_f32_e32 v117, v149
	s_waitcnt lgkmcnt(1)
	v_mfma_f32_32x32x16_bf16 v[80:95], v[106:109], v[102:105], v[80:95]
	s_waitcnt lgkmcnt(0)
	v_mfma_f32_32x32x16_bf16 v[64:79], v[110:113], v[102:105], v[64:79]
	ds_read_b128 v[102:105], v201 offset:49152
	ds_read_b128 v[106:109], v201 offset:57344
	v_exp_f32_e32 v110, v158
	v_exp_f32_e32 v111, v159
	v_exp_f32_e32 v112, v154
	v_exp_f32_e32 v113, v155
	s_waitcnt lgkmcnt(1)
	v_mfma_f32_32x32x16_bf16 v[80:95], v[102:105], v[98:101], v[80:95]
	s_waitcnt lgkmcnt(0)
	v_mfma_f32_32x32x16_bf16 v[64:79], v[106:109], v[98:101], v[64:79]
	v_add_f32_e32 v98, 0, v163
	v_add_f32_e32 v98, v177, v98
	v_add_f32_e32 v98, v164, v98
	v_add_f32_e32 v98, v207, v98
	v_add_f32_e32 v98, v176, v98
	v_add_f32_e32 v98, v210, v98
	v_add_f32_e32 v98, v165, v98
	v_add_f32_e32 v98, v175, v98
	v_add_f32_e32 v98, v166, v98
	v_add_f32_e32 v98, v173, v98
	v_add_f32_e32 v98, v167, v98
	v_add_f32_e32 v98, v174, v98
	v_exp_f32_e32 v108, v160
	v_add_f32_e32 v98, v168, v98
	v_exp_f32_e32 v109, v161
	v_add_f32_e32 v98, v171, v98
	v_add_f32_e32 v98, v169, v98
	v_add_f32_e32 v98, v172, v98
	v_add_f32_e32 v98, v108, v98
	v_add_f32_e32 v98, v109, v98
	v_add_f32_e32 v98, v110, v98
	v_add_f32_e32 v98, v111, v98
	v_add_f32_e32 v98, v112, v98
	v_add_f32_e32 v98, v113, v98
	v_add_f32_e32 v98, v114, v98
	v_add_f32_e32 v98, v115, v98
	v_add_f32_e32 v98, v116, v98
	v_add_f32_e32 v98, v117, v98
	v_add_f32_e32 v98, v118, v98
	v_add_f32_e32 v98, v119, v98
	v_add_f32_e32 v98, v120, v98
	v_add_f32_e32 v98, v121, v98
	v_add_f32_e32 v98, v122, v98
	v_add_f32_e32 v98, v123, v98
	v_mov_b32_e32 v99, v98
	v_cvt_pk_bf16_f32 v100, v163, v177
	v_cvt_pk_bf16_f32 v101, v164, v207
	v_cvt_pk_bf16_f32 v102, v176, v210
	v_cvt_pk_bf16_f32 v103, v165, v175
	s_nop 1
	v_permlane32_swap_b32_e32 v98, v99
	v_cvt_pk_bf16_f32 v104, v166, v173
	v_cvt_pk_bf16_f32 v105, v167, v174
	v_cvt_pk_bf16_f32 v106, v168, v171
	v_cvt_pk_bf16_f32 v107, v169, v172
	v_cvt_pk_bf16_f32 v108, v108, v109
	v_cvt_pk_bf16_f32 v109, v110, v111
	v_cvt_pk_bf16_f32 v110, v112, v113
	v_cvt_pk_bf16_f32 v111, v114, v115
	v_cvt_pk_bf16_f32 v112, v116, v117
	v_cvt_pk_bf16_f32 v113, v118, v119
	v_cvt_pk_bf16_f32 v114, v120, v121
	v_cvt_pk_bf16_f32 v115, v122, v123
	s_nop 0
	ds_read_b64_tr_b16 v[116:117], v187 offset:0
	ds_read_b64_tr_b16 v[118:119], v187 offset:0x800
	ds_read_b64_tr_b16 v[120:121], v187 offset:0x1000
	ds_read_b64_tr_b16 v[122:123], v187 offset:0x1800
	ds_read_b64_tr_b16 v[124:125], v187 offset:0x2000
	ds_read_b64_tr_b16 v[126:127], v187 offset:0x2800
	ds_read_b64_tr_b16 v[128:129], v187 offset:0x3000
	ds_read_b64_tr_b16 v[130:131], v187 offset:0x3800
	s_waitcnt lgkmcnt(0)
	s_nop 0
	v_mfma_f32_32x32x16_bf16 v[0:15], v[100:103], v[116:119], v[0:15]
	ds_read_b64_tr_b16 v[116:117], v187 offset:0x200
	ds_read_b64_tr_b16 v[118:119], v187 offset:0xa00
	v_mfma_f32_32x32x16_bf16 v[0:15], v[104:107], v[120:123], v[0:15]
	ds_read_b64_tr_b16 v[120:121], v187 offset:0x1200
	ds_read_b64_tr_b16 v[122:123], v187 offset:0x1a00
	v_mfma_f32_32x32x16_bf16 v[0:15], v[108:111], v[124:127], v[0:15]
	ds_read_b64_tr_b16 v[124:125], v187 offset:0x2200
	ds_read_b64_tr_b16 v[126:127], v187 offset:0x2a00
	v_mfma_f32_32x32x16_bf16 v[0:15], v[112:115], v[128:131], v[0:15]
	ds_read_b64_tr_b16 v[128:129], v187 offset:0x3200
	ds_read_b64_tr_b16 v[130:131], v187 offset:0x3a00
	s_waitcnt lgkmcnt(0)
	v_mfma_f32_32x32x16_bf16 v[48:63], v[100:103], v[116:119], v[48:63]
	ds_read_b64_tr_b16 v[116:117], v187 offset:0x400
	ds_read_b64_tr_b16 v[118:119], v187 offset:0xc00
	v_mfma_f32_32x32x16_bf16 v[48:63], v[104:107], v[120:123], v[48:63]
	ds_read_b64_tr_b16 v[120:121], v187 offset:0x1400
	ds_read_b64_tr_b16 v[122:123], v187 offset:0x1c00
	v_mfma_f32_32x32x16_bf16 v[48:63], v[108:111], v[124:127], v[48:63]
	ds_read_b64_tr_b16 v[124:125], v187 offset:0x2400
	ds_read_b64_tr_b16 v[126:127], v187 offset:0x2c00
	v_mfma_f32_32x32x16_bf16 v[48:63], v[112:115], v[128:131], v[48:63]
	ds_read_b64_tr_b16 v[128:129], v187 offset:0x3400
	ds_read_b64_tr_b16 v[130:131], v187 offset:0x3c00
	s_waitcnt lgkmcnt(0)
	v_mfma_f32_32x32x16_bf16 v[32:47], v[100:103], v[116:119], v[32:47]
	ds_read_b64_tr_b16 v[116:117], v187 offset:0x600
	ds_read_b64_tr_b16 v[118:119], v187 offset:0xe00
	v_mfma_f32_32x32x16_bf16 v[32:47], v[104:107], v[120:123], v[32:47]
	ds_read_b64_tr_b16 v[120:121], v187 offset:0x1600
	ds_read_b64_tr_b16 v[122:123], v187 offset:0x1e00
	v_mfma_f32_32x32x16_bf16 v[32:47], v[108:111], v[124:127], v[32:47]
	ds_read_b64_tr_b16 v[124:125], v187 offset:0x2600
	ds_read_b64_tr_b16 v[126:127], v187 offset:0x2e00
	v_mfma_f32_32x32x16_bf16 v[32:47], v[112:115], v[128:131], v[32:47]
	ds_read_b64_tr_b16 v[128:129], v187 offset:0x3600
	ds_read_b64_tr_b16 v[130:131], v187 offset:0x3e00
	s_waitcnt lgkmcnt(0)
	v_mfma_f32_32x32x16_bf16 v[16:31], v[100:103], v[116:119], v[16:31]
	v_max_f32_e32 v100, v81, v81
	v_max_f32_e32 v101, v80, v80
	v_max_f32_e32 v100, v101, v100
	v_max3_f32 v100, v100, v82, v83
	v_max3_f32 v100, v100, v84, v85
	v_max3_f32 v100, v100, v86, v87
	v_max3_f32 v100, v100, v88, v89
	v_max3_f32 v100, v100, v90, v91
	v_max3_f32 v100, v100, v92, v93
	v_mfma_f32_32x32x16_bf16 v[16:31], v[104:107], v[120:123], v[16:31]
	v_max3_f32 v100, v100, v94, v95
	v_max3_f32 v100, v100, v64, v65
	v_max3_f32 v100, v100, v66, v67
	v_max3_f32 v100, v100, v68, v69
	v_max3_f32 v100, v100, v70, v71
	v_max3_f32 v100, v100, v72, v73
	v_max3_f32 v100, v100, v74, v75
	v_max3_f32 v100, v100, v76, v77
	v_mfma_f32_32x32x16_bf16 v[16:31], v[108:111], v[124:127], v[16:31]
	v_max3_f32 v100, v100, v78, v79
	v_mov_b32_e32 v101, v100
	s_nop 1
	v_permlane32_swap_b32_e32 v100, v101
	v_max_f32_e32 v101, v101, v101
	v_max_f32_e32 v100, v100, v100
	v_max_f32_e32 v100, v100, v101
	v_sub_f32_e32 v101, v100, v170
	v_cmp_ge_f32_e32 vcc, s92, v101
	v_max_f32_e32 v101, v170, v170
	v_max_f32_e32 v101, v101, v100
	v_mfma_f32_32x32x16_bf16 v[16:31], v[112:115], v[128:131], v[16:31]
	v_sub_f32_e32 v100, v170, v101
	v_mul_f32_e32 v100, 0x3e0293ee, v100
	v_exp_f32_e32 v100, v100
	s_cmp_eq_u64 vcc, exec
	s_cselect_b64 s[42:43], -1, 0
	v_cndmask_b32_e64 v100, v100, 1.0, s[42:43]
	v_cmp_gt_f32_e32 vcc, 1.0, v100
	s_barrier
	s_cbranch_vccz .LBB0_542
	s_and_saveexec_b64 s[6:7], s[40:41]
	ds_write_b32 v184, v100 offset:128
	s_or_b64 exec, exec, s[6:7]
	s_waitcnt lgkmcnt(0)
	ds_read_b128 v[102:105], v182 offset:224
	ds_read_b128 v[106:109], v182 offset:192
	ds_read_b128 v[110:113], v182 offset:160
	ds_read_b128 v[114:117], v182 offset:128
	s_waitcnt lgkmcnt(3)
	v_pk_mul_f32 v[14:15], v[14:15], v[104:105]
	s_waitcnt lgkmcnt(2)
	v_pk_mul_f32 v[10:11], v[10:11], v[108:109]
	s_waitcnt lgkmcnt(1)
	v_pk_mul_f32 v[6:7], v[6:7], v[112:113]
	s_waitcnt lgkmcnt(0)
	v_pk_mul_f32 v[2:3], v[2:3], v[116:117]
	v_pk_mul_f32 v[12:13], v[12:13], v[102:103]
	v_pk_mul_f32 v[8:9], v[8:9], v[106:107]
	v_pk_mul_f32 v[4:5], v[4:5], v[110:111]
	v_pk_mul_f32 v[0:1], v[0:1], v[114:115]
	v_pk_mul_f32 v[62:63], v[62:63], v[104:105]
	v_pk_mul_f32 v[58:59], v[58:59], v[108:109]
	v_pk_mul_f32 v[54:55], v[54:55], v[112:113]
	v_pk_mul_f32 v[50:51], v[50:51], v[116:117]
	v_pk_mul_f32 v[60:61], v[60:61], v[102:103]
	v_pk_mul_f32 v[56:57], v[56:57], v[106:107]
	v_pk_mul_f32 v[52:53], v[52:53], v[110:111]
	v_pk_mul_f32 v[48:49], v[48:49], v[114:115]
	v_pk_mul_f32 v[46:47], v[46:47], v[104:105]
	v_pk_mul_f32 v[42:43], v[42:43], v[108:109]
	v_pk_mul_f32 v[38:39], v[38:39], v[112:113]
	v_pk_mul_f32 v[34:35], v[34:35], v[116:117]
	v_pk_mul_f32 v[44:45], v[44:45], v[102:103]
	v_pk_mul_f32 v[40:41], v[40:41], v[106:107]
	v_pk_mul_f32 v[36:37], v[36:37], v[110:111]
	v_pk_mul_f32 v[32:33], v[32:33], v[114:115]
	v_pk_mul_f32 v[30:31], v[30:31], v[104:105]
	v_pk_mul_f32 v[26:27], v[26:27], v[108:109]
	v_pk_mul_f32 v[22:23], v[22:23], v[112:113]
	v_pk_mul_f32 v[18:19], v[18:19], v[116:117]
	v_pk_mul_f32 v[28:29], v[28:29], v[102:103]
	v_pk_mul_f32 v[24:25], v[24:25], v[106:107]
	v_pk_mul_f32 v[20:21], v[20:21], v[110:111]
	v_pk_mul_f32 v[16:17], v[16:17], v[114:115]
